# hyena units rebalanced: blocks with two diff-attention units run 3 hyena units, blocks with one run 5
# baseline (speedup 1.0000x reference)
.LBB0_1038:
	s_cmpk_lg_i32 s95, 0x100
	s_cbranch_scc1 .Lhyb_std
	s_cmpk_ge_i32 s56, 0x400
	s_cbranch_scc1 .Lhyb_std
	s_cmpk_lt_i32 s56, 0x200
	s_cbranch_scc1 .Lhyb_std
	s_and_b32 s2, s56, 0xff
	s_cmpk_ge_i32 s56, 0x300
	s_cbranch_scc1 .Lhyb_k3
	s_cmpk_lt_i32 s2, 0x80
	s_cbranch_scc0 .Lhyb_std
	s_addk_i32 s56, 0x200
	s_branch .Lhyb_chk
.Lhyb_k3:
	s_cmpk_lt_i32 s2, 0x80
	s_cbranch_scc1 .Lhyb_after_extra
	s_sub_i32 s56, s56, 0x80
	s_branch .Lhyb_chk
.Lhyb_after_extra:
	s_addk_i32 s56, 0x180
	s_branch .Lhyb_chk

.Lhyb_chk:
	s_cmp_ge_i32 s56, s4
	s_cbranch_scc1 .LBB0_1229
